# prompt attention: 8 dwordx2 row stores per lane -> 4 dwordx4 via v_permlane32_swap; latch wait vmcnt(4)
# speedup vs baseline: 1.0017x; 1.0014x over previous
; #define LAS __attribute__((address_space(3)))
; __device__ __forceinline__ void attn_prompt_phase(const Frame& F, const Args& A) {
;     ...
;     for (int u = lo; u < hi; ++u) {
;         __syncthreads();
;         rot = cont ? (rot + 8 >= 12 ? rot - 4 : rot + 8) : 0;
;         { const int r0 = cont ? 128 : 0, nch = cont ? 4 : 6;
; #pragma unroll
;           for (int i = 0; i < 6; ++i) if (i < nch) { const int ci = tid + 512 * i, rl = r0 + (ci >> 3), c8 = ci & 7; int sl = rot + (rl >> 5); sl = sl >= 12 ? sl - 12 : sl;
;               const int row = sl * 32 + (rl & 31); *(LAS v4u*)(AK + row * KS_ + 16 * c8) = pk[i]; *(LAS v4u*)(AV + row * KS_ + 16 * c8) = pv[i]; } }
;         bf16x8 qf[4];
; #pragma unroll
;         for (int s = 0; s < 4; ++s) qf[s] = qn[s];
;         const AttnU C = U;
.LBB0_1160:
	s_or_b64 exec, exec, s[8:9]
	s_waitcnt vmcnt(4)
	v_mov_b64_e32 v[6:7], v[130:131]
	v_mov_b64_e32 v[34:35], v[122:123]
	v_mov_b64_e32 v[38:39], v[118:119]
	v_mov_b64_e32 v[42:43], v[66:67]
	s_add_i32 s62, s62, 32
	s_and_b64 vcc, exec, s[68:69]
	v_mov_b64_e32 v[8:9], v[132:133]
	v_mov_b64_e32 v[36:37], v[124:125]
	v_mov_b64_e32 v[40:41], v[120:121]
	v_mov_b64_e32 v[44:45], v[68:69]
	s_mov_b32 s10, s82
	s_mov_b64 s[64:65], s[60:61]
	s_mov_b32 s43, s90
	s_mov_b32 s0, s86
	s_mov_b32 s79, s83
	s_mov_b32 s42, s87
	v_readlane_b32 s83, v254, 32
	s_cbranch_vccnz .LBB0_1218

; __device__ __forceinline__ void attn_prompt_phase(const Frame& F, const Args& A) {
;     ...
;         for (int kt = 0; kt < 5; ++kt) {
;             if (kt >= tfirst) {
;                 f32x16 S;
; #pragma unroll
;                 for (int i = 0; i < 16; ++i) S[i] = 0.f;
;                 int sl = rot + w + kt; sl = sl >= 12 ? sl - 12 : sl;
;                 LAS unsigned char* kp = AK + (32 * sl + r32) * KS_ + 16 * hh;
;                 bf16x8 kf[4]; s16x4 vlo0[2], vhi0[2], vlo1[2], vhi1[2];
; #pragma unroll
;                 for (int s = 0; s < 4; ++s) kf[s] = *(LAS bf16x8*)(kp + 32 * s);
; #pragma unroll
;                 for (int s2 = 0; s2 < 2; ++s2) { LAS unsigned char* va = AV + (32 * sl + 16 * s2 + 4 * hh + qq) * KS_ + (16 * cb16 + 4 * pp) * 2;
;                     vlo0[s2] = trr(va); vhi0[s2] = trr(va + 8 * KS_); vlo1[s2] = trr(va + 64); vhi1[s2] = trr(va + 8 * KS_ + 64); }
;                 __builtin_amdgcn_sched_barrier(0);
; #pragma unroll
;                 for (int s = 0; s < 4; ++s) S = MFMA32(kf[s], qf[s], S);
; #pragma unroll
;                 for (int rr = 0; rr < 16; ++rr) { const int keyrow = (rr & 3) + 8 * (rr >> 2) + 4 * hh; float p = ex2(S[rr] - m); if (kt == 0 && keyrow < r32o) p = 0.f; if (kt == 4 && keyrow > r32o) p = 0.f; S[rr] = p; lsum += p; }
; #pragma unroll
;                 for (int s2 = 0; s2 < 2; ++s2) {
;                     const bf16x8 pf = packf8(S[8 * s2], S[8 * s2 + 1], S[8 * s2 + 2], S[8 * s2 + 3], S[8 * s2 + 4], S[8 * s2 + 5], S[8 * s2 + 6], S[8 * s2 + 7]);
;                     O0 = MFMA32(cat8(vlo0[s2], vhi0[s2]), pf, O0);
;                     O1 = MFMA32(cat8(vlo1[s2], vhi1[s2]), pf, O1);
;                 }
;             }
;         }
;         lsum += __shfl_xor(lsum, 32);
;         const float inv = 1.0f / lsum;
;         const size_t orow = C.tokbase + (size_t)C.dil * (C.k0 + 128 + 32 * w + r32);
;         bf16* op = (bf16*)(ws + WS_AOG) + (size_t)C.g * AOG_STRIDE + orow * 512 + C.h * 64 + 4 * hh;
; #pragma unroll
;         for (int q4 = 0; q4 < 4; ++q4) {
;             v2u o; o.x = pg8::cvt_pk_bf16(O0[4 * q4] * inv, O0[4 * q4 + 1] * inv); o.y = pg8::cvt_pk_bf16(O0[4 * q4 + 2] * inv, O0[4 * q4 + 3] * inv);
;             *(GAS v2u*)(op + 8 * q4) = o;
;             v2u o2; o2.x = pg8::cvt_pk_bf16(O1[4 * q4] * inv, O1[4 * q4 + 1] * inv); o2.y = pg8::cvt_pk_bf16(O1[4 * q4 + 2] * inv, O1[4 * q4 + 3] * inv);
.LBB0_1214:
	ds_read_b128 v[98:101], v73
	ds_read_b128 v[186:189], v73 offset:32
	ds_read_b128 v[190:193], v73 offset:64
	ds_read_b128 v[194:197], v73 offset:96
	v_add_u32_e32 v73, s91, v159
	v_mad_u64_u32 v[102:103], s[46:47], v73, s3, v[148:149]
	ds_read_b64_tr_b16 v[198:199], v102 offset:55296
	ds_read_b64_tr_b16 v[200:201], v102 offset:56448
	ds_read_b64_tr_b16 v[204:205], v102 offset:56512
	ds_read_b64_tr_b16 v[202:203], v102 offset:55360
	ds_read_b64_tr_b16 v[206:207], v102 offset:57600
	ds_read_b64_tr_b16 v[208:209], v102 offset:58752
	ds_read_b64_tr_b16 v[212:213], v102 offset:58816
	ds_read_b64_tr_b16 v[210:211], v102 offset:57664
	s_waitcnt lgkmcnt(11)
	v_mfma_f32_32x32x16_bf16 v[98:113], v[98:101], v[42:45], 0
	s_lshl_b32 s4, s42, 7
	s_waitcnt lgkmcnt(10)
	v_mfma_f32_32x32x16_bf16 v[98:113], v[186:189], v[38:41], v[98:113]
	s_waitcnt lgkmcnt(9)
	v_mfma_f32_32x32x16_bf16 v[98:113], v[190:193], v[34:37], v[98:113]
	s_waitcnt lgkmcnt(8)
	v_mfma_f32_32x32x16_bf16 v[98:113], v[194:197], v[6:9], v[98:113]
	s_nop 11
	v_sub_f32_e32 v6, v98, v71
	v_sub_f32_e32 v7, v99, v71
	v_sub_f32_e32 v8, v100, v71
	v_sub_f32_e32 v9, v101, v71
	v_sub_f32_e32 v34, v102, v71
	v_sub_f32_e32 v35, v103, v71
	v_sub_f32_e32 v36, v104, v71
	v_sub_f32_e32 v37, v105, v71
	v_exp_f32_e32 v6, v6
	v_exp_f32_e32 v7, v7
	v_exp_f32_e32 v8, v8
	v_exp_f32_e32 v9, v9
	v_exp_f32_e32 v34, v34
	v_exp_f32_e32 v35, v35
	v_exp_f32_e32 v36, v36
	v_exp_f32_e32 v37, v37
	v_cndmask_b32_e64 v42, v6, 0, s[8:9]
	v_sub_f32_e32 v6, v110, v71
	v_cndmask_b32_e64 v43, 0, v7, s[10:11]
	v_cndmask_b32_e64 v44, v8, 0, s[18:19]
	v_cndmask_b32_e64 v45, v9, 0, s[20:21]
	v_cndmask_b32_e64 v73, v34, 0, s[22:23]
	v_cndmask_b32_e64 v98, v35, 0, s[24:25]
	v_cndmask_b32_e64 v99, v36, 0, s[28:29]
	v_cndmask_b32_e64 v100, v37, 0, s[30:31]
	v_exp_f32_e32 v34, v6
	v_cvt_pk_bf16_f32 v6, v42, v43
	v_cvt_pk_bf16_f32 v7, v44, v45
	v_cvt_pk_bf16_f32 v8, v73, v98
	v_cvt_pk_bf16_f32 v9, v99, v100
	v_sub_f32_e32 v38, v106, v71
	s_waitcnt lgkmcnt(6)
	v_mfma_f32_32x32x16_bf16 v[14:29], v[198:201], v[6:9], v[14:29]
	v_sub_f32_e32 v39, v107, v71
	v_exp_f32_e32 v38, v38
	v_sub_f32_e32 v40, v108, v71
	v_exp_f32_e32 v39, v39
	v_sub_f32_e32 v41, v109, v71
	v_exp_f32_e32 v40, v40
	v_exp_f32_e32 v41, v41
	s_waitcnt lgkmcnt(4)
	v_mfma_f32_32x32x16_bf16 v[50:65], v[202:205], v[6:9], v[50:65]
	v_add_f32_e32 v9, v185, v42
	v_add_f32_e32 v9, v43, v9
	v_add_f32_e32 v9, v44, v9
	v_add_f32_e32 v9, v45, v9
	v_add_f32_e32 v9, v73, v9
	v_add_f32_e32 v9, v98, v9
	v_add_f32_e32 v9, v99, v9
	v_cndmask_b32_e64 v38, v38, 0, s[34:35]
	v_cndmask_b32_e64 v101, v34, 0, s[26:27]
	v_sub_f32_e32 v34, v111, v71
	v_add_f32_e32 v9, v100, v9
	v_cndmask_b32_e64 v39, v39, 0, s[36:37]
	v_exp_f32_e32 v34, v34
	v_sub_f32_e32 v35, v112, v71
	v_sub_f32_e32 v36, v113, v71
	v_add_f32_e32 v9, v38, v9
	v_cndmask_b32_e64 v40, v40, 0, s[38:39]
	v_exp_f32_e32 v35, v35
	v_exp_f32_e32 v36, v36
	v_add_f32_e32 v9, v39, v9
	v_cndmask_b32_e64 v41, v41, 0, s[40:41]
	v_add_f32_e32 v9, v40, v9
	v_add_f32_e32 v9, v41, v9
	v_cndmask_b32_e64 v6, v34, 0, s[12:13]
	v_add_f32_e32 v9, v101, v9
	v_cndmask_b32_e64 v7, v35, 0, s[14:15]
	v_cndmask_b32_e64 v8, v36, 0, s[16:17]
	v_cvt_pk_bf16_f32 v34, v38, v39
	v_cvt_pk_bf16_f32 v35, v40, v41
	v_cvt_pk_bf16_f32 v36, v101, v6
	v_add_f32_e32 v6, v6, v9
	v_add_f32_e32 v6, v7, v6
	v_add_f32_e32 v6, v8, v6
	v_cvt_pk_bf16_f32 v37, v7, v8
	ds_bpermute_b32 v7, v72, v6
	s_waitcnt lgkmcnt(3)
	v_mfma_f32_32x32x16_bf16 v[14:29], v[206:209], v[34:37], v[14:29]
	s_waitcnt lgkmcnt(0)
	v_add_f32_e32 v8, v6, v7
	v_div_scale_f32 v6, s[8:9], v8, v8, 1.0
	v_rcp_f32_e32 v7, v6
	v_mfma_f32_32x32x16_bf16 v[50:65], v[210:213], v[34:37], v[50:65]
	v_fma_f32 v9, -v6, v7, 1.0
	v_fmac_f32_e32 v7, v9, v7
	v_div_scale_f32 v9, vcc, 1.0, v8, 1.0
	v_mul_f32_e32 v34, v9, v7
	v_fma_f32 v35, -v6, v34, v9
	v_fmac_f32_e32 v34, v35, v7
	v_fma_f32 v6, -v6, v34, v9
	v_div_fmas_f32 v6, v6, v7, v34
	v_div_fixup_f32 v9, v6, v8, 1.0
	v_add_u32_e32 v34, s0, v158
	v_mov_b64_e32 v[6:7], s[64:65]
	v_mad_u64_u32 v[6:7], s[8:9], v34, s43, v[6:7]
	v_ashrrev_i32_e32 v35, 31, v34
	v_mov_b32_e32 v34, v7
	v_mad_u64_u32 v[34:35], s[8:9], v35, s43, v[34:35]
	v_mov_b32_e32 v7, v34
	v_mad_i64_i32 v[34:35], s[8:9], s79, v183, v[150:151]
	v_lshlrev_b64 v[36:37], 10, v[6:7]
	v_lshl_add_u64 v[34:35], v[34:35], 0, v[36:37]
	v_lshl_add_u64 v[34:35], v[34:35], 0, s[4:5]
	v_lshl_add_u64 v[34:35], v[146:147], 1, v[34:35]
	v_mbcnt_lo_u32_b32 v36, -1, 0
	v_mbcnt_hi_u32_b32 v36, -1, v36
	v_and_b32_e32 v36, 32, v36
	v_lshrrev_b32_e32 v36, 2, v36
	v_mov_b32_e32 v37, 0
	v_lshl_add_u64 v[34:35], v[34:35], 0, v[36:37]
	v_mul_f32_e32 v36, v14, v9
	v_mul_f32_e32 v37, v15, v9
	v_cvt_pk_bf16_f32 v14, v36, v37
	v_mul_f32_e32 v36, v16, v9
	v_mul_f32_e32 v37, v17, v9
	v_cvt_pk_bf16_f32 v15, v36, v37
	v_mul_f32_e32 v36, v18, v9
	v_mul_f32_e32 v37, v19, v9
	v_cvt_pk_bf16_f32 v16, v36, v37
	v_mul_f32_e32 v36, v20, v9
	v_mul_f32_e32 v37, v21, v9
	v_cvt_pk_bf16_f32 v17, v36, v37
	s_nop 1
	v_permlane32_swap_b32_e32 v14, v16
	v_permlane32_swap_b32_e32 v15, v17
	global_store_dwordx4 v[34:35], v[14:17], off
	v_mul_f32_e32 v36, v22, v9
	v_mul_f32_e32 v37, v23, v9
	v_cvt_pk_bf16_f32 v22, v36, v37
	v_mul_f32_e32 v36, v24, v9
	v_mul_f32_e32 v37, v25, v9
	v_cvt_pk_bf16_f32 v23, v36, v37
	v_mul_f32_e32 v36, v26, v9
	v_mul_f32_e32 v37, v27, v9
	v_cvt_pk_bf16_f32 v24, v36, v37
	v_mul_f32_e32 v36, v28, v9
	v_mul_f32_e32 v37, v29, v9
	v_cvt_pk_bf16_f32 v25, v36, v37
	s_nop 1
	v_permlane32_swap_b32_e32 v22, v24
	v_permlane32_swap_b32_e32 v23, v25
	global_store_dwordx4 v[34:35], v[22:25], off offset:32
	v_mul_f32_e32 v36, v50, v9
	v_mul_f32_e32 v37, v51, v9
	v_cvt_pk_bf16_f32 v18, v36, v37
	v_mul_f32_e32 v36, v52, v9
	v_mul_f32_e32 v37, v53, v9
	v_cvt_pk_bf16_f32 v19, v36, v37
	v_mul_f32_e32 v36, v54, v9
	v_mul_f32_e32 v37, v55, v9
	v_cvt_pk_bf16_f32 v20, v36, v37
	v_mul_f32_e32 v36, v56, v9
	v_mul_f32_e32 v37, v57, v9
	v_cvt_pk_bf16_f32 v21, v36, v37
	s_nop 1
	v_permlane32_swap_b32_e32 v18, v20
	v_permlane32_swap_b32_e32 v19, v21
	global_store_dwordx4 v[34:35], v[18:21], off offset:64
	v_mul_f32_e32 v36, v58, v9
	v_mul_f32_e32 v37, v59, v9
	v_cvt_pk_bf16_f32 v26, v36, v37
	v_mul_f32_e32 v36, v60, v9
	v_mul_f32_e32 v37, v61, v9
	v_cvt_pk_bf16_f32 v27, v36, v37
	v_mul_f32_e32 v36, v62, v9
	v_mul_f32_e32 v37, v63, v9
	v_cvt_pk_bf16_f32 v28, v36, v37
	v_mul_f32_e32 v36, v64, v9
	v_mul_f32_e32 v37, v65, v9
	v_cvt_pk_bf16_f32 v29, v36, v37
	s_nop 1
	v_permlane32_swap_b32_e32 v26, v28
	v_permlane32_swap_b32_e32 v27, v29
	global_store_dwordx4 v[34:35], v[26:29], off offset:96
	s_and_saveexec_b64 s[8:9], s[6:7]
	s_cbranch_execz .LBB0_1160
	v_log_f32_e32 v14, v8
	v_mad_i64_i32 v[8:9], s[10:11], s79, v184, v[152:153]
	v_lshlrev_b64 v[6:7], 5, v[6:7]
	s_mov_b32 s43, s5
	v_lshl_add_u64 v[6:7], v[8:9], 0, v[6:7]
	v_add_f32_e32 v14, v71, v14
	v_lshl_add_u64 v[6:7], s[42:43], 2, v[6:7]
	global_store_dword v[6:7], v14, off
	s_branch .LBB0_1160
